# XN2 row loop: all 8 row loads issued up front with nt policy (same treatment as XN1)
# speedup vs baseline: 1.0072x; 1.0036x over previous
; __device__ __forceinline__ unsigned pk2(float lo, float hi) { unsigned r; asm volatile("v_cvt_pk_bf16_f32 %0, %1, %2" : "=v"(r) : "v"(lo), "v"(hi)); return r; }
; __device__ __forceinline__ void xn_phase(const Params& p, int layer, int which, char* smem) {
;     ...
;     for (int row = blockIdx.x * 8 + wid; row < nrows; row += gridDim.x * 8) {
;         const bool isc = row >= SEQ; const float* src = isc ? csrc + (size_t)(row - SEQ) * DM : lsrc + (size_t)row * DM;
;         const float* sh = sv + (isc ? 4096 : 0); const float* sc = sh + 2048;
;         f32x4 v[8]; float ss = 0.f;
; #pragma unroll
;         for (int j = 0; j < 8; ++j) { v[j] = *(const f32x4*)(src + 4 * (lane + 64 * j)); ss += (v[j][0] * v[j][0] + v[j][1] * v[j][1]) + (v[j][2] * v[j][2] + v[j][3] * v[j][3]); }
;         const float rinv = rsqrtf(wave_sum(ss) * (1.f / DM) + 1e-6f);
; #pragma unroll
;         for (int j = 0; j < 8; ++j) { const int c = 4 * (lane + 64 * j); const f32x4 gg = *(const f32x4*)(g + c); float y[4];
; #pragma unroll
;             for (int e = 0; e < 4; ++e) y[e] = v[j][e] * rinv * gg[e] * (1.f + sc[c + e]) + sh[c + e];
;             u32x2 o; o.x = pk2(y[0], y[1]); o.y = pk2(y[2], y[3]); *(u32x2*)(XN + (size_t)row * DM + c) = o; }
.LBB0_1334:
	s_or_b64 exec, exec, s[14:15]
	v_mov_b32_e32 v51, v1
	v_mov_b32_e32 v53, v1
	v_lshl_add_u64 v[70:71], v[2:3], 0, v[50:51]
	v_lshl_add_u64 v[36:37], v[2:3], 0, v[52:53]
	global_load_dwordx4 v[30:33], v[70:71], off nt
	global_load_dwordx4 v[26:29], v[70:71], off offset:1024 nt
	global_load_dwordx4 v[22:25], v[70:71], off offset:2048 nt
	global_load_dwordx4 v[18:21], v[70:71], off offset:3072 nt
	global_load_dwordx4 v[14:17], v[36:37], off nt
	global_load_dwordx4 v[10:13], v[36:37], off offset:1024 nt
	global_load_dwordx4 v[6:9], v[36:37], off offset:2048 nt
	global_load_dwordx4 v[2:5], v[36:37], off offset:3072 nt
	v_mov_b32_e32 v55, v1
	v_mov_b32_e32 v57, v1
	v_mov_b32_e32 v59, v1
	s_mov_b32 s0, 0x800000
	v_add_u32_e32 v0, s95, v0
	v_lshlrev_b64 v[60:61], 12, v[34:35]
	s_waitcnt vmcnt(0)
	v_mul_f32_e32 v36, v30, v30
	v_mul_f32_e32 v37, v31, v31
	v_mul_f32_e32 v70, v32, v32
	v_mul_f32_e32 v71, v33, v33
	v_fmac_f32_e32 v36, v26, v26
	v_fmac_f32_e32 v37, v27, v27
	v_fmac_f32_e32 v70, v28, v28
	v_fmac_f32_e32 v71, v29, v29
	v_fmac_f32_e32 v36, v22, v22
	v_fmac_f32_e32 v37, v23, v23
	v_fmac_f32_e32 v70, v24, v24
	v_fmac_f32_e32 v71, v25, v25
	v_fmac_f32_e32 v36, v18, v18
	v_fmac_f32_e32 v37, v19, v19
	v_fmac_f32_e32 v70, v20, v20
	v_fmac_f32_e32 v71, v21, v21
	v_fmac_f32_e32 v36, v14, v14
	v_fmac_f32_e32 v37, v15, v15
	v_fmac_f32_e32 v70, v16, v16
	v_fmac_f32_e32 v71, v17, v17
	v_fmac_f32_e32 v36, v10, v10
	v_fmac_f32_e32 v37, v11, v11
	v_fmac_f32_e32 v70, v12, v12
	v_fmac_f32_e32 v71, v13, v13
	v_fmac_f32_e32 v36, v6, v6
	v_fmac_f32_e32 v37, v7, v7
	v_fmac_f32_e32 v70, v8, v8
	v_fmac_f32_e32 v71, v9, v9
	v_fmac_f32_e32 v36, v2, v2
	v_fmac_f32_e32 v37, v3, v3
	v_fmac_f32_e32 v70, v4, v4
	v_fmac_f32_e32 v71, v5, v5
	v_add_f32_e32 v36, v36, v37
	v_add_f32_e32 v70, v70, v71
	v_add_f32_e32 v36, v36, v70
	ds_bpermute_b32 v37, v62, v36
	s_waitcnt lgkmcnt(0)
	v_add_f32_e32 v36, v36, v37
	ds_bpermute_b32 v37, v63, v36
	s_waitcnt lgkmcnt(0)
	v_add_f32_e32 v36, v36, v37
	ds_bpermute_b32 v37, v64, v36
	s_waitcnt lgkmcnt(0)
	v_add_f32_e32 v36, v36, v37
	ds_bpermute_b32 v37, v65, v36
	s_waitcnt lgkmcnt(0)
	v_add_f32_e32 v36, v36, v37
	ds_bpermute_b32 v37, v66, v36
	s_waitcnt lgkmcnt(0)
	v_add_f32_e32 v36, v36, v37
	ds_bpermute_b32 v37, v67, v36
	s_waitcnt lgkmcnt(0)
	v_add_f32_e32 v36, v36, v37
	v_fmamk_f32 v36, v36, 0x3a000000, v199
	v_cmp_gt_f32_e32 vcc, s0, v36
	v_mul_f32_e32 v37, 0x4b800000, v36
	s_nop 0
	v_cndmask_b32_e32 v36, v36, v37, vcc
	v_rsq_f32_e32 v36, v36
	s_nop 0
	v_mul_f32_e32 v37, 0x45800000, v36
	v_cndmask_b32_e32 v51, v36, v37, vcc
	global_load_dwordx4 v[34:37], v[38:39], off
	v_mul_f32_e32 v30, v30, v51
	v_mul_f32_e32 v31, v31, v51
	v_mul_f32_e32 v32, v32, v51
	v_mul_f32_e32 v26, v26, v51
	v_mul_f32_e32 v27, v27, v51
	v_mul_f32_e32 v28, v28, v51
	v_mul_f32_e32 v29, v29, v51
	v_mul_f32_e32 v22, v22, v51
	v_mul_f32_e32 v23, v23, v51
	v_mul_f32_e32 v24, v24, v51
	v_mul_f32_e32 v25, v25, v51
	v_mul_f32_e32 v18, v18, v51
	v_mul_f32_e32 v19, v19, v51
	v_mul_f32_e32 v20, v20, v51
	v_mul_f32_e32 v21, v21, v51
	v_mul_f32_e32 v14, v14, v51
	v_mul_f32_e32 v15, v15, v51
	v_mul_f32_e32 v16, v16, v51
	v_mul_f32_e32 v17, v17, v51
	v_mul_f32_e32 v10, v10, v51
	v_mul_f32_e32 v11, v11, v51
	v_mul_f32_e32 v12, v12, v51
	v_mul_f32_e32 v13, v13, v51
	v_mul_f32_e32 v6, v6, v51
	v_mul_f32_e32 v7, v7, v51
	v_mul_f32_e32 v8, v8, v51
	v_mul_f32_e32 v9, v9, v51
	v_mul_f32_e32 v2, v2, v51
	v_mul_f32_e32 v3, v3, v51
	v_mul_f32_e32 v4, v4, v51
	v_mul_f32_e32 v5, v5, v51
	v_cmp_le_i32_e32 vcc, s30, v0
	s_or_b64 s[6:7], vcc, s[6:7]
	s_waitcnt vmcnt(0)
	v_mul_f32_e32 v30, v34, v30
	v_lshl_add_u32 v34, v69, 2, v68
	ds_read_b128 v[70:73], v34 offset:8192
	ds_read_b128 v[74:77], v34
	v_mul_f32_e32 v31, v35, v31
	v_mul_f32_e32 v32, v36, v32
	s_waitcnt lgkmcnt(1)
	v_add_f32_e32 v35, 1.0, v71
	s_waitcnt lgkmcnt(0)
	v_fma_f32 v31, v35, v31, v75
	v_add_f32_e32 v35, 1.0, v72
	v_add_f32_e32 v53, 1.0, v70
	v_fma_f32 v35, v35, v32, v76
	v_mul_f32_e32 v32, v33, v51
	v_fma_f32 v30, v53, v30, v74
	v_mul_f32_e32 v32, v37, v32
	v_add_f32_e32 v33, 1.0, v73
	v_fmac_f32_e32 v77, v33, v32
	v_cvt_pk_bf16_f32 v32, v30, v31
	v_lshl_add_u64 v[30:31], v[48:49], 0, v[60:61]
	v_cvt_pk_bf16_f32 v33, v35, v77
	global_store_dwordx2 v[30:31], v[32:33], off
	global_load_dwordx4 v[70:73], v[38:39], off offset:1024
	ds_read_b128 v[74:77], v34 offset:9216
	ds_read_b128 v[78:81], v34 offset:1024
	s_waitcnt lgkmcnt(1)
	v_add_f32_e32 v32, 1.0, v74
	s_waitcnt vmcnt(0)
; __device__ __forceinline__ unsigned pk2(float lo, float hi) { unsigned r; asm volatile("v_cvt_pk_bf16_f32 %0, %1, %2" : "=v"(r) : "v"(lo), "v"(hi)); return r; }
; __device__ __forceinline__ void xn_phase(const Params& p, int layer, int which, char* smem) {
;     ...
;         for (int j = 0; j < 8; ++j) { const int c = 4 * (lane + 64 * j); const f32x4 gg = *(const f32x4*)(g + c); float y[4];
; #pragma unroll
;             for (int e = 0; e < 4; ++e) y[e] = v[j][e] * rinv * gg[e] * (1.f + sc[c + e]) + sh[c + e];
;             u32x2 o; o.x = pk2(y[0], y[1]); o.y = pk2(y[2], y[3]); *(u32x2*)(XN + (size_t)row * DM + c) = o; }
	v_mul_f32_e32 v26, v26, v70
	s_waitcnt lgkmcnt(0)
	v_fma_f32 v26, v32, v26, v78
	v_mul_f32_e32 v27, v27, v71
	v_add_f32_e32 v32, 1.0, v75
	v_fma_f32 v27, v27, v32, v79
	v_mul_f32_e32 v28, v28, v72
	v_add_f32_e32 v32, 1.0, v76
	v_fma_f32 v28, v28, v32, v80
	v_mul_f32_e32 v29, v29, v73
	v_add_f32_e32 v32, 1.0, v77
	v_fmac_f32_e32 v81, v29, v32
	v_cvt_pk_bf16_f32 v26, v26, v27
	v_cvt_pk_bf16_f32 v27, v28, v81
	global_store_dwordx2 v[30:31], v[26:27], off offset:512
	global_load_dwordx4 v[26:29], v[38:39], off offset:2048
	ds_read_b128 v[70:73], v34 offset:10240
	ds_read_b128 v[74:77], v34 offset:2048
	s_waitcnt vmcnt(0)
	v_mul_f32_e32 v22, v22, v26
	s_waitcnt lgkmcnt(1)
	v_add_f32_e32 v26, 1.0, v70
	s_waitcnt lgkmcnt(0)
	v_fma_f32 v22, v26, v22, v74
	v_mul_f32_e32 v23, v23, v27
	v_add_f32_e32 v26, 1.0, v71
	v_fma_f32 v23, v23, v26, v75
	v_mul_f32_e32 v24, v24, v28
	v_add_f32_e32 v26, 1.0, v72
	v_fma_f32 v24, v24, v26, v76
	v_mul_f32_e32 v25, v25, v29
	v_add_f32_e32 v26, 1.0, v73
	v_fmac_f32_e32 v77, v25, v26
	v_cvt_pk_bf16_f32 v22, v22, v23
	v_cvt_pk_bf16_f32 v23, v24, v77
	global_store_dwordx2 v[30:31], v[22:23], off offset:1024
	global_load_dwordx4 v[22:25], v[38:39], off offset:3072
	ds_read_b128 v[26:29], v34 offset:11264
	ds_read_b128 v[70:73], v34 offset:3072
	s_waitcnt vmcnt(0)
	v_mul_f32_e32 v18, v18, v22
	s_waitcnt lgkmcnt(1)
	v_add_f32_e32 v22, 1.0, v26
	s_waitcnt lgkmcnt(0)
	v_fma_f32 v18, v22, v18, v70
	v_mul_f32_e32 v19, v19, v23
	v_add_f32_e32 v22, 1.0, v27
	v_fma_f32 v19, v19, v22, v71
	v_mul_f32_e32 v20, v20, v24
	v_add_f32_e32 v22, 1.0, v28
	v_fma_f32 v20, v20, v22, v72
	v_mul_f32_e32 v21, v21, v25
	v_add_f32_e32 v22, 1.0, v29
	v_fmac_f32_e32 v73, v21, v22
	v_cvt_pk_bf16_f32 v18, v18, v19
	v_cvt_pk_bf16_f32 v19, v20, v73
	global_store_dwordx2 v[30:31], v[18:19], off offset:1536
	global_load_dwordx4 v[18:21], v[40:41], off
	ds_read_b128 v[22:25], v34 offset:12288
	ds_read_b128 v[26:29], v34 offset:4096
	s_waitcnt vmcnt(0)
	v_mul_f32_e32 v14, v14, v18
	s_waitcnt lgkmcnt(1)
	v_add_f32_e32 v18, 1.0, v22
	s_waitcnt lgkmcnt(0)
	v_fma_f32 v14, v18, v14, v26
	v_mul_f32_e32 v15, v15, v19
	v_add_f32_e32 v18, 1.0, v23
	v_fma_f32 v15, v15, v18, v27
	v_mul_f32_e32 v16, v16, v20
	v_add_f32_e32 v18, 1.0, v24
	v_fma_f32 v16, v16, v18, v28
	v_mul_f32_e32 v17, v17, v21
	v_add_f32_e32 v18, 1.0, v25
	v_fmac_f32_e32 v29, v17, v18
	v_cvt_pk_bf16_f32 v14, v14, v15
	v_cvt_pk_bf16_f32 v15, v16, v29
	global_store_dwordx2 v[30:31], v[14:15], off offset:2048
	global_load_dwordx4 v[14:17], v[42:43], off
	ds_read_b128 v[18:21], v34 offset:13312
	ds_read_b128 v[22:25], v34 offset:5120
	s_waitcnt vmcnt(0)
	v_mul_f32_e32 v10, v10, v14
	s_waitcnt lgkmcnt(1)
	v_add_f32_e32 v14, 1.0, v18
	s_waitcnt lgkmcnt(0)
	v_fma_f32 v10, v14, v10, v22
	v_mul_f32_e32 v11, v11, v15
	v_add_f32_e32 v14, 1.0, v19
	v_fma_f32 v11, v11, v14, v23
	v_mul_f32_e32 v12, v12, v16
	v_add_f32_e32 v14, 1.0, v20
	v_fma_f32 v12, v12, v14, v24
	v_mul_f32_e32 v13, v13, v17
	v_add_f32_e32 v14, 1.0, v21
	v_fmac_f32_e32 v25, v13, v14
	v_cvt_pk_bf16_f32 v10, v10, v11
	v_cvt_pk_bf16_f32 v11, v12, v25
	global_store_dwordx2 v[30:31], v[10:11], off offset:2560
	global_load_dwordx4 v[10:13], v[44:45], off
	ds_read_b128 v[14:17], v34 offset:14336
	ds_read_b128 v[18:21], v34 offset:6144
	s_waitcnt vmcnt(0)
	v_mul_f32_e32 v6, v6, v10
	s_waitcnt lgkmcnt(1)
	v_add_f32_e32 v10, 1.0, v14
	s_waitcnt lgkmcnt(0)
	v_fma_f32 v6, v10, v6, v18
	v_mul_f32_e32 v7, v7, v11
	v_add_f32_e32 v10, 1.0, v15
	v_fma_f32 v7, v7, v10, v19
	v_mul_f32_e32 v8, v8, v12
	v_add_f32_e32 v10, 1.0, v16
	v_fma_f32 v8, v8, v10, v20
	v_mul_f32_e32 v9, v9, v13
	v_add_f32_e32 v10, 1.0, v17
	v_fmac_f32_e32 v21, v9, v10
	v_cvt_pk_bf16_f32 v6, v6, v7
	v_cvt_pk_bf16_f32 v7, v8, v21
	global_store_dwordx2 v[30:31], v[6:7], off offset:3072
	global_load_dwordx4 v[6:9], v[46:47], off
	ds_read_b128 v[10:13], v34 offset:15360
	ds_read_b128 v[14:17], v34 offset:7168
	s_waitcnt vmcnt(0)
	v_mul_f32_e32 v2, v2, v6
	s_waitcnt lgkmcnt(1)
	v_add_f32_e32 v6, 1.0, v10
	s_waitcnt lgkmcnt(0)
	v_fma_f32 v2, v6, v2, v14
	v_mul_f32_e32 v3, v3, v7
	v_add_f32_e32 v6, 1.0, v11
	v_fma_f32 v3, v3, v6, v15
	v_mul_f32_e32 v4, v4, v8
	v_add_f32_e32 v6, 1.0, v12
	v_fma_f32 v4, v4, v6, v16
	v_mul_f32_e32 v5, v5, v9
	v_add_f32_e32 v6, 1.0, v13
	v_fmac_f32_e32 v17, v5, v6
	v_cvt_pk_bf16_f32 v2, v2, v3
	v_cvt_pk_bf16_f32 v3, v4, v17
	global_store_dwordx2 v[30:31], v[2:3], off offset:3584
	s_andn2_b64 exec, exec, s[6:7]
	s_cbranch_execz .LBB0_1339
